# as v48 plus: redundant workgroup barrier at the end of each attention unit removed (the work-queue fetch barrier follows)
# speedup vs baseline: 1.0011x; 1.0011x over previous
; DI unsigned pk2(float a, float b) { f32x2 v = {a, b}; bf2_t r = __builtin_convertvector(v, bf2_t); return __builtin_bit_cast(unsigned, r); }
; DI void attn_unit(const Params& p, int l, int b, int qtp, int grp, char* smem) {
;     ...
;   const int gcol = (grp == 2 ? 0 : grp == 1 ? 256 : grp == 0 ? 512 : 768) + w * 64 + 4 * h;
;   bf16_t* mrow = (bf16_t*)(p.ws + OFF_MIX) + (tok0 + qpos) * DM + gcol;
; #pragma unroll
;   for (int g = 0; g < 4; ++g) {
;     u32x2 a = {pk2(o0[4 * g], o0[4 * g + 1]), pk2(o0[4 * g + 2], o0[4 * g + 3])};
;     u32x2 c = {pk2(o1[4 * g], o1[4 * g + 1]), pk2(o1[4 * g + 2], o1[4 * g + 3])};
;     *(u32x2*)(mrow + 8 * g) = a;
;     *(u32x2*)(mrow + 32 + 8 * g) = c;
;   }
;   __syncthreads();
.Lpf3_skip:
	s_mov_b64 exec, -1
	v_readlane_b32 s1, v244, 21
	s_cmp_lg_u32 s1, 1
	s_cselect_b32 s2, s0, 0x100
	v_readlane_b32 s0, v244, 9
	v_readlane_b32 s1, v244, 10
	s_and_b64 s[0:1], s[0:1], exec
	s_cselect_b32 s0, 0, s2
	v_or3_b32 v0, v159, v220, s0
	v_readlane_b32 s0, v246, 16
	v_lshlrev_b64 v[34:35], 11, v[156:157]
	v_readlane_b32 s1, v246, 17
	s_waitcnt vmcnt(0)
	v_lshl_add_u64 v[34:35], s[0:1], 0, v[34:35]
	v_lshl_add_u64 v[34:35], v[0:1], 1, v[34:35]
	v_cvt_pk_bf16_f32 v36, v18, v19
	v_cvt_pk_bf16_f32 v37, v20, v21
	v_cvt_pk_bf16_f32 v38, v22, v23
	v_cvt_pk_bf16_f32 v39, v24, v25
	v_cvt_pk_bf16_f32 v40, v26, v27
	v_cvt_pk_bf16_f32 v41, v28, v29
	v_cvt_pk_bf16_f32 v42, v30, v31
	v_cvt_pk_bf16_f32 v43, v32, v33
	v_cvt_pk_bf16_f32 v44, v2, v3
	v_cvt_pk_bf16_f32 v45, v4, v5
	v_cvt_pk_bf16_f32 v46, v6, v7
	v_cvt_pk_bf16_f32 v47, v8, v9
	v_cvt_pk_bf16_f32 v48, v10, v11
	v_cvt_pk_bf16_f32 v49, v12, v13
	v_cvt_pk_bf16_f32 v50, v14, v15
	v_cvt_pk_bf16_f32 v51, v16, v17
	v_and_b32_e32 v52, 32, v203
	v_lshrrev_b32_e32 v52, 2, v52
	v_mov_b32_e32 v53, 0
	v_lshl_add_u64 v[34:35], v[34:35], 0, v[52:53]
	v_permlane32_swap_b32_e32 v36, v38
	v_permlane32_swap_b32_e32 v37, v39
	v_permlane32_swap_b32_e32 v40, v42
	v_permlane32_swap_b32_e32 v41, v43
	v_permlane32_swap_b32_e32 v44, v46
	v_permlane32_swap_b32_e32 v45, v47
	v_permlane32_swap_b32_e32 v48, v50
	v_permlane32_swap_b32_e32 v49, v51
	global_store_dwordx4 v[34:35], v[36:39], off
	global_store_dwordx4 v[34:35], v[40:43], off offset:32
	global_store_dwordx4 v[34:35], v[44:47], off offset:64
	global_store_dwordx4 v[34:35], v[48:51], off offset:96
	s_nop 0
